# FFN-out residual epilogue de-serialised: 3-deep software pipeline over its 16 pieces with counted vmcnt(6) waits instead of the one-piece-ahead ladder
# baseline (speedup 1.0000x reference)
.LBB0_352:
	s_andn2_b64 vcc, exec, s[8:9]
	s_cbranch_vccnz .LBB0_386
	v_lshl_or_b32 v190, s5, 8, v210
	s_lshr_b32 s5, s55, 5
	s_mul_i32 s8, s5, 0x1800
	s_ashr_i32 s9, s8, 31
	s_lshl_b64 s[8:9], s[8:9], 2
	v_readlane_b32 s5, v241, 61
	s_add_u32 s64, s5, s8
	v_readlane_b32 s5, v241, 62
	s_addc_u32 s65, s5, s9
	v_readlane_b32 s5, v241, 63
	v_ashrrev_i32_e32 v191, 31, v190
	s_add_u32 s8, s5, s8
	v_readlane_b32 s5, v240, 0
	v_lshlrev_b64 v[128:129], 2, v[190:191]
	s_addc_u32 s9, s5, s9
	v_lshl_add_u64 v[132:133], s[64:65], 0, v[128:129]
	v_lshl_add_u64 v[140:141], s[8:9], 0, v[128:129]
	global_load_dwordx4 v[144:147], v[132:133], off offset:16
	global_load_dwordx4 v[148:151], v[132:133], off
	global_load_dwordx4 v[152:155], v[140:141], off offset:16
	global_load_dwordx4 v[156:159], v[140:141], off
	global_load_dwordx4 v[128:131], v[132:133], off offset:528
	s_nop 0
	global_load_dwordx4 v[132:135], v[132:133], off offset:512
	s_nop 0
	global_load_dwordx4 v[136:139], v[140:141], off offset:528
	s_nop 0
	global_load_dwordx4 v[140:143], v[140:141], off offset:512
	v_lshl_add_u32 v192, s55, 8, v205
	v_ashrrev_i32_e32 v193, 31, v192
	v_lshlrev_b64 v[160:161], 10, v[192:193]
	v_lshl_add_u64 v[198:199], v[160:161], 0, v[190:191]
	v_lshl_add_u64 v[194:195], v[198:199], 2, s[0:1]
	global_load_dwordx4 v[160:163], v[194:195], off offset:16
	global_load_dwordx4 v[164:167], v[194:195], off
	v_readlane_b32 s36, v241, 8
	v_readlane_b32 s37, v241, 9
	s_andn2_b64 vcc, exec, s[36:37]
	v_lshl_add_u64 v[196:197], v[198:199], 1, s[52:53]
	v_cndmask_b32_e64 v168, 0, 1, s[36:37]
	v_cmp_ne_u32_e64 s[8:9], 1, v168
	s_cbranch_vccnz .LBB0_355
	v_lshlrev_b32_e32 v199, 1, v198
	v_lshlrev_b32_e32 v198, 2, v198
	s_mov_b64 s[64:65], s[0:1]
	s_mov_b64 s[8:9], s[52:53]
	s_mov_b64 s[36:37], s[26:27]
	global_load_dwordx4 v[212:215], v199, s[8:9] offset:0
	global_load_dwordx4 v[216:219], v198, s[64:65] offset:512
	global_load_dwordx4 v[220:223], v198, s[64:65] offset:528
	global_load_dwordx4 v[224:227], v199, s[8:9] offset:256
	s_add_u32 s64, s64, 65536
	s_addc_u32 s65, s65, 0
	s_add_u32 s8, s8, 32768
	s_addc_u32 s9, s9, 0
	global_load_dwordx4 v[228:231], v198, s[64:65] offset:0
	global_load_dwordx4 v[232:235], v198, s[64:65] offset:16
	global_load_dwordx4 v[236:239], v199, s[8:9] offset:0
	s_waitcnt vmcnt(6)
	v_lshlrev_b32_e32 v194, 16, v212
	v_and_b32_e32 v195, 0xffff0000, v212
	v_lshlrev_b32_e32 v196, 16, v213
	v_and_b32_e32 v197, 0xffff0000, v213
	v_lshlrev_b32_e32 v190, 16, v214
	v_and_b32_e32 v191, 0xffff0000, v214
	v_lshlrev_b32_e32 v192, 16, v215
	v_and_b32_e32 v193, 0xffff0000, v215
	v_pk_fma_f32 v[164:165], v[156:157], v[194:195], v[164:165]
	v_pk_fma_f32 v[166:167], v[158:159], v[196:197], v[166:167]
	v_pk_fma_f32 v[160:161], v[152:153], v[190:191], v[160:161]
	v_pk_fma_f32 v[162:163], v[154:155], v[192:193], v[162:163]
	v_pk_fma_f32 v[124:125], v[124:125], v[148:149], v[164:165]
	v_pk_fma_f32 v[126:127], v[126:127], v[150:151], v[166:167]
	v_pk_fma_f32 v[120:121], v[120:121], v[144:145], v[160:161]
	v_pk_fma_f32 v[122:123], v[122:123], v[146:147], v[162:163]
	global_store_dwordx4 v198, v[124:127], s[36:37] offset:0
	global_store_dwordx4 v198, v[120:123], s[36:37] offset:16
	global_load_dwordx4 v[164:167], v198, s[64:65] offset:512
	global_load_dwordx4 v[160:163], v198, s[64:65] offset:528
	global_load_dwordx4 v[212:215], v199, s[8:9] offset:256
	s_waitcnt vmcnt(6)
	v_lshlrev_b32_e32 v194, 16, v224
	v_and_b32_e32 v195, 0xffff0000, v224
	v_lshlrev_b32_e32 v196, 16, v225
	v_and_b32_e32 v197, 0xffff0000, v225
	v_lshlrev_b32_e32 v190, 16, v226
	v_and_b32_e32 v191, 0xffff0000, v226
	v_lshlrev_b32_e32 v192, 16, v227
	v_and_b32_e32 v193, 0xffff0000, v227
	v_pk_fma_f32 v[216:217], v[140:141], v[194:195], v[216:217]
	v_pk_fma_f32 v[218:219], v[142:143], v[196:197], v[218:219]
	v_pk_fma_f32 v[220:221], v[136:137], v[190:191], v[220:221]
	v_pk_fma_f32 v[222:223], v[138:139], v[192:193], v[222:223]
	v_pk_fma_f32 v[116:117], v[116:117], v[132:133], v[216:217]
	v_pk_fma_f32 v[118:119], v[118:119], v[134:135], v[218:219]
	v_pk_fma_f32 v[112:113], v[112:113], v[128:129], v[220:221]
	v_pk_fma_f32 v[114:115], v[114:115], v[130:131], v[222:223]
	global_store_dwordx4 v198, v[116:119], s[36:37] offset:512
	global_store_dwordx4 v198, v[112:115], s[36:37] offset:528
	s_add_u32 s36, s36, 65536
	s_addc_u32 s37, s37, 0
	s_add_u32 s64, s64, 65536
	s_addc_u32 s65, s65, 0
	s_add_u32 s8, s8, 32768
	s_addc_u32 s9, s9, 0
	global_load_dwordx4 v[216:219], v198, s[64:65] offset:0
	global_load_dwordx4 v[220:223], v198, s[64:65] offset:16
	global_load_dwordx4 v[224:227], v199, s[8:9] offset:0
	s_waitcnt vmcnt(6)
	v_lshlrev_b32_e32 v194, 16, v236
	v_and_b32_e32 v195, 0xffff0000, v236
	v_lshlrev_b32_e32 v196, 16, v237
	v_and_b32_e32 v197, 0xffff0000, v237
	v_lshlrev_b32_e32 v190, 16, v238
	v_and_b32_e32 v191, 0xffff0000, v238
	v_lshlrev_b32_e32 v192, 16, v239
	v_and_b32_e32 v193, 0xffff0000, v239
	v_pk_fma_f32 v[228:229], v[156:157], v[194:195], v[228:229]
	v_pk_fma_f32 v[230:231], v[158:159], v[196:197], v[230:231]
	v_pk_fma_f32 v[232:233], v[152:153], v[190:191], v[232:233]
	v_pk_fma_f32 v[234:235], v[154:155], v[192:193], v[234:235]
	v_pk_fma_f32 v[108:109], v[108:109], v[148:149], v[228:229]
	v_pk_fma_f32 v[110:111], v[110:111], v[150:151], v[230:231]
	v_pk_fma_f32 v[104:105], v[104:105], v[144:145], v[232:233]
	v_pk_fma_f32 v[106:107], v[106:107], v[146:147], v[234:235]
	global_store_dwordx4 v198, v[108:111], s[36:37] offset:0
	global_store_dwordx4 v198, v[104:107], s[36:37] offset:16
	global_load_dwordx4 v[228:231], v198, s[64:65] offset:512
	global_load_dwordx4 v[232:235], v198, s[64:65] offset:528
	global_load_dwordx4 v[236:239], v199, s[8:9] offset:256
	s_waitcnt vmcnt(6)
	v_lshlrev_b32_e32 v194, 16, v212
	v_and_b32_e32 v195, 0xffff0000, v212
	v_lshlrev_b32_e32 v196, 16, v213
	v_and_b32_e32 v197, 0xffff0000, v213
	v_lshlrev_b32_e32 v190, 16, v214
	v_and_b32_e32 v191, 0xffff0000, v214
	v_lshlrev_b32_e32 v192, 16, v215
	v_and_b32_e32 v193, 0xffff0000, v215
	v_pk_fma_f32 v[164:165], v[140:141], v[194:195], v[164:165]
	v_pk_fma_f32 v[166:167], v[142:143], v[196:197], v[166:167]
	v_pk_fma_f32 v[160:161], v[136:137], v[190:191], v[160:161]
	v_pk_fma_f32 v[162:163], v[138:139], v[192:193], v[162:163]
	v_pk_fma_f32 v[100:101], v[100:101], v[132:133], v[164:165]
	v_pk_fma_f32 v[102:103], v[102:103], v[134:135], v[166:167]
	v_pk_fma_f32 v[96:97], v[96:97], v[128:129], v[160:161]
	v_pk_fma_f32 v[98:99], v[98:99], v[130:131], v[162:163]
	global_store_dwordx4 v198, v[100:103], s[36:37] offset:512
	global_store_dwordx4 v198, v[96:99], s[36:37] offset:528
	s_add_u32 s36, s36, 65536
	s_addc_u32 s37, s37, 0
	s_add_u32 s64, s64, 65536
	s_addc_u32 s65, s65, 0
	s_add_u32 s8, s8, 32768
	s_addc_u32 s9, s9, 0
	global_load_dwordx4 v[164:167], v198, s[64:65] offset:0
	global_load_dwordx4 v[160:163], v198, s[64:65] offset:16
	global_load_dwordx4 v[212:215], v199, s[8:9] offset:0
	s_waitcnt vmcnt(6)
	v_lshlrev_b32_e32 v194, 16, v224
	v_and_b32_e32 v195, 0xffff0000, v224
	v_lshlrev_b32_e32 v196, 16, v225
	v_and_b32_e32 v197, 0xffff0000, v225
	v_lshlrev_b32_e32 v190, 16, v226
	v_and_b32_e32 v191, 0xffff0000, v226
	v_lshlrev_b32_e32 v192, 16, v227
	v_and_b32_e32 v193, 0xffff0000, v227
	v_pk_fma_f32 v[216:217], v[156:157], v[194:195], v[216:217]
	v_pk_fma_f32 v[218:219], v[158:159], v[196:197], v[218:219]
	v_pk_fma_f32 v[220:221], v[152:153], v[190:191], v[220:221]
	v_pk_fma_f32 v[222:223], v[154:155], v[192:193], v[222:223]
	v_pk_fma_f32 v[92:93], v[92:93], v[148:149], v[216:217]
	v_pk_fma_f32 v[94:95], v[94:95], v[150:151], v[218:219]
	v_pk_fma_f32 v[88:89], v[88:89], v[144:145], v[220:221]
	v_pk_fma_f32 v[90:91], v[90:91], v[146:147], v[222:223]
	global_store_dwordx4 v198, v[92:95], s[36:37] offset:0
	global_store_dwordx4 v198, v[88:91], s[36:37] offset:16
	global_load_dwordx4 v[216:219], v198, s[64:65] offset:512
	global_load_dwordx4 v[220:223], v198, s[64:65] offset:528
	global_load_dwordx4 v[224:227], v199, s[8:9] offset:256
	s_waitcnt vmcnt(6)
	v_lshlrev_b32_e32 v194, 16, v236
	v_and_b32_e32 v195, 0xffff0000, v236
	v_lshlrev_b32_e32 v196, 16, v237
	v_and_b32_e32 v197, 0xffff0000, v237
	v_lshlrev_b32_e32 v190, 16, v238
	v_and_b32_e32 v191, 0xffff0000, v238
	v_lshlrev_b32_e32 v192, 16, v239
	v_and_b32_e32 v193, 0xffff0000, v239
	v_pk_fma_f32 v[228:229], v[140:141], v[194:195], v[228:229]
	v_pk_fma_f32 v[230:231], v[142:143], v[196:197], v[230:231]
	v_pk_fma_f32 v[232:233], v[136:137], v[190:191], v[232:233]
	v_pk_fma_f32 v[234:235], v[138:139], v[192:193], v[234:235]
	v_pk_fma_f32 v[84:85], v[84:85], v[132:133], v[228:229]
	v_pk_fma_f32 v[86:87], v[86:87], v[134:135], v[230:231]
	v_pk_fma_f32 v[80:81], v[80:81], v[128:129], v[232:233]
	v_pk_fma_f32 v[82:83], v[82:83], v[130:131], v[234:235]
	global_store_dwordx4 v198, v[84:87], s[36:37] offset:512
	global_store_dwordx4 v198, v[80:83], s[36:37] offset:528
	s_add_u32 s36, s36, 65536
	s_addc_u32 s37, s37, 0
	s_add_u32 s64, s64, 327680
	s_addc_u32 s65, s65, 0
	s_add_u32 s8, s8, 163840
	s_addc_u32 s9, s9, 0
	global_load_dwordx4 v[228:231], v198, s[64:65] offset:0
	global_load_dwordx4 v[232:235], v198, s[64:65] offset:16
	global_load_dwordx4 v[236:239], v199, s[8:9] offset:0
	s_waitcnt vmcnt(6)
	v_lshlrev_b32_e32 v194, 16, v212
	v_and_b32_e32 v195, 0xffff0000, v212
	v_lshlrev_b32_e32 v196, 16, v213
	v_and_b32_e32 v197, 0xffff0000, v213
	v_lshlrev_b32_e32 v190, 16, v214
	v_and_b32_e32 v191, 0xffff0000, v214
	v_lshlrev_b32_e32 v192, 16, v215
	v_and_b32_e32 v193, 0xffff0000, v215
	v_pk_fma_f32 v[164:165], v[156:157], v[194:195], v[164:165]
	v_pk_fma_f32 v[166:167], v[158:159], v[196:197], v[166:167]
	v_pk_fma_f32 v[160:161], v[152:153], v[190:191], v[160:161]
	v_pk_fma_f32 v[162:163], v[154:155], v[192:193], v[162:163]
	v_pk_fma_f32 v[76:77], v[76:77], v[148:149], v[164:165]
	v_pk_fma_f32 v[78:79], v[78:79], v[150:151], v[166:167]
	v_pk_fma_f32 v[72:73], v[72:73], v[144:145], v[160:161]
	v_pk_fma_f32 v[74:75], v[74:75], v[146:147], v[162:163]
	global_store_dwordx4 v198, v[76:79], s[36:37] offset:0
	global_store_dwordx4 v198, v[72:75], s[36:37] offset:16
	global_load_dwordx4 v[164:167], v198, s[64:65] offset:512
	global_load_dwordx4 v[160:163], v198, s[64:65] offset:528
	global_load_dwordx4 v[212:215], v199, s[8:9] offset:256
	s_waitcnt vmcnt(6)
	v_lshlrev_b32_e32 v194, 16, v224
	v_and_b32_e32 v195, 0xffff0000, v224
	v_lshlrev_b32_e32 v196, 16, v225
	v_and_b32_e32 v197, 0xffff0000, v225
	v_lshlrev_b32_e32 v190, 16, v226
	v_and_b32_e32 v191, 0xffff0000, v226
	v_lshlrev_b32_e32 v192, 16, v227
	v_and_b32_e32 v193, 0xffff0000, v227
	v_pk_fma_f32 v[216:217], v[140:141], v[194:195], v[216:217]
	v_pk_fma_f32 v[218:219], v[142:143], v[196:197], v[218:219]
	v_pk_fma_f32 v[220:221], v[136:137], v[190:191], v[220:221]
	v_pk_fma_f32 v[222:223], v[138:139], v[192:193], v[222:223]
	v_pk_fma_f32 v[68:69], v[68:69], v[132:133], v[216:217]
	v_pk_fma_f32 v[70:71], v[70:71], v[134:135], v[218:219]
	v_pk_fma_f32 v[64:65], v[64:65], v[128:129], v[220:221]
	v_pk_fma_f32 v[66:67], v[66:67], v[130:131], v[222:223]
	global_store_dwordx4 v198, v[68:71], s[36:37] offset:512
	global_store_dwordx4 v198, v[64:67], s[36:37] offset:528
	s_add_u32 s36, s36, 327680
	s_addc_u32 s37, s37, 0
	s_add_u32 s64, s64, 65536
	s_addc_u32 s65, s65, 0
	s_add_u32 s8, s8, 32768
	s_addc_u32 s9, s9, 0
	global_load_dwordx4 v[216:219], v198, s[64:65] offset:0
	global_load_dwordx4 v[220:223], v198, s[64:65] offset:16
	global_load_dwordx4 v[224:227], v199, s[8:9] offset:0
	s_waitcnt vmcnt(6)
	v_lshlrev_b32_e32 v194, 16, v236
	v_and_b32_e32 v195, 0xffff0000, v236
	v_lshlrev_b32_e32 v196, 16, v237
	v_and_b32_e32 v197, 0xffff0000, v237
	v_lshlrev_b32_e32 v190, 16, v238
	v_and_b32_e32 v191, 0xffff0000, v238
	v_lshlrev_b32_e32 v192, 16, v239
	v_and_b32_e32 v193, 0xffff0000, v239
	v_pk_fma_f32 v[228:229], v[156:157], v[194:195], v[228:229]
	v_pk_fma_f32 v[230:231], v[158:159], v[196:197], v[230:231]
	v_pk_fma_f32 v[232:233], v[152:153], v[190:191], v[232:233]
	v_pk_fma_f32 v[234:235], v[154:155], v[192:193], v[234:235]
	v_pk_fma_f32 v[60:61], v[60:61], v[148:149], v[228:229]
	v_pk_fma_f32 v[62:63], v[62:63], v[150:151], v[230:231]
	v_pk_fma_f32 v[56:57], v[56:57], v[144:145], v[232:233]
	v_pk_fma_f32 v[58:59], v[58:59], v[146:147], v[234:235]
	global_store_dwordx4 v198, v[60:63], s[36:37] offset:0
	global_store_dwordx4 v198, v[56:59], s[36:37] offset:16
	global_load_dwordx4 v[228:231], v198, s[64:65] offset:512
	global_load_dwordx4 v[232:235], v198, s[64:65] offset:528
	global_load_dwordx4 v[236:239], v199, s[8:9] offset:256
	s_waitcnt vmcnt(6)
	v_lshlrev_b32_e32 v194, 16, v212
	v_and_b32_e32 v195, 0xffff0000, v212
	v_lshlrev_b32_e32 v196, 16, v213
	v_and_b32_e32 v197, 0xffff0000, v213
	v_lshlrev_b32_e32 v190, 16, v214
	v_and_b32_e32 v191, 0xffff0000, v214
	v_lshlrev_b32_e32 v192, 16, v215
	v_and_b32_e32 v193, 0xffff0000, v215
	v_pk_fma_f32 v[164:165], v[140:141], v[194:195], v[164:165]
	v_pk_fma_f32 v[166:167], v[142:143], v[196:197], v[166:167]
	v_pk_fma_f32 v[160:161], v[136:137], v[190:191], v[160:161]
	v_pk_fma_f32 v[162:163], v[138:139], v[192:193], v[162:163]
	v_pk_fma_f32 v[52:53], v[52:53], v[132:133], v[164:165]
	v_pk_fma_f32 v[54:55], v[54:55], v[134:135], v[166:167]
	v_pk_fma_f32 v[48:49], v[48:49], v[128:129], v[160:161]
	v_pk_fma_f32 v[50:51], v[50:51], v[130:131], v[162:163]
	global_store_dwordx4 v198, v[52:55], s[36:37] offset:512
	global_store_dwordx4 v198, v[48:51], s[36:37] offset:528
	s_add_u32 s36, s36, 65536
	s_addc_u32 s37, s37, 0
	s_add_u32 s64, s64, 65536
	s_addc_u32 s65, s65, 0
	s_add_u32 s8, s8, 32768
	s_addc_u32 s9, s9, 0
	global_load_dwordx4 v[164:167], v198, s[64:65] offset:0
	global_load_dwordx4 v[160:163], v198, s[64:65] offset:16
	global_load_dwordx4 v[212:215], v199, s[8:9] offset:0
	s_waitcnt vmcnt(6)
	v_lshlrev_b32_e32 v194, 16, v224
	v_and_b32_e32 v195, 0xffff0000, v224
	v_lshlrev_b32_e32 v196, 16, v225
	v_and_b32_e32 v197, 0xffff0000, v225
	v_lshlrev_b32_e32 v190, 16, v226
	v_and_b32_e32 v191, 0xffff0000, v226
	v_lshlrev_b32_e32 v192, 16, v227
	v_and_b32_e32 v193, 0xffff0000, v227
	v_pk_fma_f32 v[216:217], v[156:157], v[194:195], v[216:217]
	v_pk_fma_f32 v[218:219], v[158:159], v[196:197], v[218:219]
	v_pk_fma_f32 v[220:221], v[152:153], v[190:191], v[220:221]
	v_pk_fma_f32 v[222:223], v[154:155], v[192:193], v[222:223]
	v_pk_fma_f32 v[44:45], v[44:45], v[148:149], v[216:217]
	v_pk_fma_f32 v[46:47], v[46:47], v[150:151], v[218:219]
	v_pk_fma_f32 v[40:41], v[40:41], v[144:145], v[220:221]
	v_pk_fma_f32 v[42:43], v[42:43], v[146:147], v[222:223]
	global_store_dwordx4 v198, v[44:47], s[36:37] offset:0
	global_store_dwordx4 v198, v[40:43], s[36:37] offset:16
	global_load_dwordx4 v[216:219], v198, s[64:65] offset:512
	global_load_dwordx4 v[220:223], v198, s[64:65] offset:528
	global_load_dwordx4 v[224:227], v199, s[8:9] offset:256
	s_waitcnt vmcnt(6)
	v_lshlrev_b32_e32 v194, 16, v236
	v_and_b32_e32 v195, 0xffff0000, v236
	v_lshlrev_b32_e32 v196, 16, v237
	v_and_b32_e32 v197, 0xffff0000, v237
	v_lshlrev_b32_e32 v190, 16, v238
	v_and_b32_e32 v191, 0xffff0000, v238
	v_lshlrev_b32_e32 v192, 16, v239
	v_and_b32_e32 v193, 0xffff0000, v239
	v_pk_fma_f32 v[228:229], v[140:141], v[194:195], v[228:229]
	v_pk_fma_f32 v[230:231], v[142:143], v[196:197], v[230:231]
	v_pk_fma_f32 v[232:233], v[136:137], v[190:191], v[232:233]
	v_pk_fma_f32 v[234:235], v[138:139], v[192:193], v[234:235]
	v_pk_fma_f32 v[36:37], v[36:37], v[132:133], v[228:229]
	v_pk_fma_f32 v[38:39], v[38:39], v[134:135], v[230:231]
	v_pk_fma_f32 v[32:33], v[32:33], v[128:129], v[232:233]
	v_pk_fma_f32 v[34:35], v[34:35], v[130:131], v[234:235]
	global_store_dwordx4 v198, v[36:39], s[36:37] offset:512
	global_store_dwordx4 v198, v[32:35], s[36:37] offset:528
	s_add_u32 s36, s36, 65536
	s_addc_u32 s37, s37, 0
	s_add_u32 s64, s64, 65536
	s_addc_u32 s65, s65, 0
	s_add_u32 s8, s8, 32768
	s_addc_u32 s9, s9, 0
	global_load_dwordx4 v[228:231], v198, s[64:65] offset:0
	global_load_dwordx4 v[232:235], v198, s[64:65] offset:16
	global_load_dwordx4 v[236:239], v199, s[8:9] offset:0
	s_waitcnt vmcnt(6)
	v_lshlrev_b32_e32 v194, 16, v212
	v_and_b32_e32 v195, 0xffff0000, v212
	v_lshlrev_b32_e32 v196, 16, v213
	v_and_b32_e32 v197, 0xffff0000, v213
	v_lshlrev_b32_e32 v190, 16, v214
	v_and_b32_e32 v191, 0xffff0000, v214
	v_lshlrev_b32_e32 v192, 16, v215
	v_and_b32_e32 v193, 0xffff0000, v215
	v_pk_fma_f32 v[164:165], v[156:157], v[194:195], v[164:165]
	v_pk_fma_f32 v[166:167], v[158:159], v[196:197], v[166:167]
	v_pk_fma_f32 v[160:161], v[152:153], v[190:191], v[160:161]
	v_pk_fma_f32 v[162:163], v[154:155], v[192:193], v[162:163]
	v_pk_fma_f32 v[28:29], v[28:29], v[148:149], v[164:165]
	v_pk_fma_f32 v[30:31], v[30:31], v[150:151], v[166:167]
	v_pk_fma_f32 v[24:25], v[24:25], v[144:145], v[160:161]
	v_pk_fma_f32 v[26:27], v[26:27], v[146:147], v[162:163]
	global_store_dwordx4 v198, v[28:31], s[36:37] offset:0
	global_store_dwordx4 v198, v[24:27], s[36:37] offset:16
	global_load_dwordx4 v[164:167], v198, s[64:65] offset:512
	global_load_dwordx4 v[160:163], v198, s[64:65] offset:528
	global_load_dwordx4 v[212:215], v199, s[8:9] offset:256
	s_waitcnt vmcnt(6)
	v_lshlrev_b32_e32 v194, 16, v224
	v_and_b32_e32 v195, 0xffff0000, v224
	v_lshlrev_b32_e32 v196, 16, v225
	v_and_b32_e32 v197, 0xffff0000, v225
	v_lshlrev_b32_e32 v190, 16, v226
	v_and_b32_e32 v191, 0xffff0000, v226
	v_lshlrev_b32_e32 v192, 16, v227
	v_and_b32_e32 v193, 0xffff0000, v227
	v_pk_fma_f32 v[216:217], v[140:141], v[194:195], v[216:217]
	v_pk_fma_f32 v[218:219], v[142:143], v[196:197], v[218:219]
	v_pk_fma_f32 v[220:221], v[136:137], v[190:191], v[220:221]
	v_pk_fma_f32 v[222:223], v[138:139], v[192:193], v[222:223]
	v_pk_fma_f32 v[20:21], v[20:21], v[132:133], v[216:217]
	v_pk_fma_f32 v[22:23], v[22:23], v[134:135], v[218:219]
	v_pk_fma_f32 v[16:17], v[16:17], v[128:129], v[220:221]
	v_pk_fma_f32 v[18:19], v[18:19], v[130:131], v[222:223]
	global_store_dwordx4 v198, v[20:23], s[36:37] offset:512
	global_store_dwordx4 v198, v[16:19], s[36:37] offset:528
	s_add_u32 s36, s36, 65536
	s_addc_u32 s37, s37, 0
	s_waitcnt vmcnt(3)
	v_lshlrev_b32_e32 v194, 16, v236
	v_and_b32_e32 v195, 0xffff0000, v236
	v_lshlrev_b32_e32 v196, 16, v237
	v_and_b32_e32 v197, 0xffff0000, v237
	v_lshlrev_b32_e32 v190, 16, v238
	v_and_b32_e32 v191, 0xffff0000, v238
	v_lshlrev_b32_e32 v192, 16, v239
	v_and_b32_e32 v193, 0xffff0000, v239
	v_pk_fma_f32 v[228:229], v[156:157], v[194:195], v[228:229]
	v_pk_fma_f32 v[230:231], v[158:159], v[196:197], v[230:231]
	v_pk_fma_f32 v[232:233], v[152:153], v[190:191], v[232:233]
	v_pk_fma_f32 v[234:235], v[154:155], v[192:193], v[234:235]
	v_pk_fma_f32 v[12:13], v[12:13], v[148:149], v[228:229]
	v_pk_fma_f32 v[14:15], v[14:15], v[150:151], v[230:231]
	v_pk_fma_f32 v[8:9], v[8:9], v[144:145], v[232:233]
	v_pk_fma_f32 v[10:11], v[10:11], v[146:147], v[234:235]
	global_store_dwordx4 v198, v[12:15], s[36:37] offset:0
	global_store_dwordx4 v198, v[8:11], s[36:37] offset:16
	s_waitcnt vmcnt(0)
	v_lshlrev_b32_e32 v194, 16, v212
	v_and_b32_e32 v195, 0xffff0000, v212
	v_lshlrev_b32_e32 v196, 16, v213
	v_and_b32_e32 v197, 0xffff0000, v213
	v_lshlrev_b32_e32 v190, 16, v214
	v_and_b32_e32 v191, 0xffff0000, v214
	v_lshlrev_b32_e32 v192, 16, v215
	v_and_b32_e32 v193, 0xffff0000, v215
	v_pk_fma_f32 v[164:165], v[140:141], v[194:195], v[164:165]
	v_pk_fma_f32 v[166:167], v[142:143], v[196:197], v[166:167]
	v_pk_fma_f32 v[160:161], v[136:137], v[190:191], v[160:161]
	v_pk_fma_f32 v[162:163], v[138:139], v[192:193], v[162:163]
	v_pk_fma_f32 v[4:5], v[4:5], v[132:133], v[164:165]
	v_pk_fma_f32 v[6:7], v[6:7], v[134:135], v[166:167]
	v_pk_fma_f32 v[0:1], v[0:1], v[128:129], v[160:161]
	v_pk_fma_f32 v[2:3], v[2:3], v[130:131], v[162:163]
	global_store_dwordx4 v198, v[4:7], s[36:37] offset:512
	global_store_dwordx4 v198, v[0:3], s[36:37] offset:528
	s_branch .LBB0_386
